# GLU epilogue: seven cache-warming loads of the other row groups' residual rows before the first dependent load
# speedup vs baseline: 1.0095x; 1.0095x over previous
.LBB0_400:
	s_mov_b64 s[24:25], 0
	s_add_u32 s42, s62, s24
	s_addc_u32 s43, s61, s25
	s_mov_b64 s[26:27], 0
	s_mov_b64 s[24:25], 0
	s_mov_b64 s[28:29], 0
	s_add_u32 s65, s17, s28
	s_addc_u32 s66, s63, s29
	s_mov_b64 s[28:29], 0
	s_add_u32 s83, s68, s28
	s_addc_u32 s84, s69, s29
	s_lshl_b32 s45, s22, 8
	s_ashr_i32 s22, s22, 3
	s_ashr_i32 s23, s22, 31
	s_mul_i32 s88, s22, 0x3000
	s_mul_hi_i32 s85, s22, 0x3000
	s_add_u32 s90, s65, s88
	v_lshl_add_u32 v172, s82, 7, v186
	s_addc_u32 s91, s66, s85
	s_lshl_b64 s[22:23], s[22:23], 12
	v_ashrrev_i32_e32 v173, 31, v172
	s_add_u32 s22, s83, s22
	v_lshlrev_b64 v[144:145], 2, v[172:173]
	s_addc_u32 s23, s84, s23
	s_mov_b64 s[28:29], 0
	v_lshl_add_u64 v[64:65], s[90:91], 0, v[144:145]
	v_lshl_add_u64 v[68:69], s[22:23], 0, v[144:145]
	global_load_dwordx4 v[72:75], v[64:65], off offset:16
	global_load_dwordx4 v[76:79], v[64:65], off
	s_nop 0
	global_load_dwordx4 v[64:67], v[68:69], off offset:16
	s_nop 0
	global_load_dwordx4 v[68:71], v[68:69], off
	v_add_u32_e32 v180, s45, v184
	v_lshl_add_u64 v[176:177], s[42:43], 0, v[144:145]
	v_ashrrev_i32_e32 v181, 31, v180
	v_cndmask_b32_e64 v144, 0, 1, s[72:73]
	v_lshlrev_b64 v[182:183], 12, v[180:181]
	v_cmp_ne_u32_e64 s[42:43], 1, v144
	s_andn2_b64 vcc, exec, s[72:73]
	s_mov_b64 s[22:23], -1
	s_cbranch_vccnz .LBB0_402
	v_lshl_add_u64 v[148:149], v[176:177], 0, v[182:183]
	v_mov_b64_e32 v[154:155], v[148:149]
	s_mov_b64 s[98:99], 0x10000
	v_lshl_add_u64 v[154:155], v[154:155], 0, s[98:99]
	global_load_dwordx4 v[144:147], v[154:155], off
	v_lshl_add_u64 v[154:155], v[154:155], 0, s[98:99]
	global_load_dwordx4 v[144:147], v[154:155], off
	v_lshl_add_u64 v[154:155], v[154:155], 0, s[98:99]
	global_load_dwordx4 v[144:147], v[154:155], off
	s_mov_b64 s[98:99], 0x50000
	v_lshl_add_u64 v[154:155], v[154:155], 0, s[98:99]
	s_mov_b64 s[98:99], 0x10000
	global_load_dwordx4 v[144:147], v[154:155], off
	v_lshl_add_u64 v[154:155], v[154:155], 0, s[98:99]
	global_load_dwordx4 v[144:147], v[154:155], off
	v_lshl_add_u64 v[154:155], v[154:155], 0, s[98:99]
	global_load_dwordx4 v[144:147], v[154:155], off
	v_lshl_add_u64 v[154:155], v[154:155], 0, s[98:99]
	global_load_dwordx4 v[144:147], v[154:155], off
	global_load_dwordx4 v[144:147], v[148:149], off offset:16
	s_nop 0
	global_load_dwordx4 v[148:151], v[148:149], off
	s_mov_b64 s[22:23], 0
.LBB0_402:
	v_lshlrev_b64 v[172:173], 1, v[172:173]
	v_sub_co_u32_e32 v174, vcc, 0, v172
	s_nop 1
	v_subb_co_u32_e32 v175, vcc, 0, v173, vcc
	s_andn2_b64 vcc, exec, s[22:23]
	v_lshl_add_u64 v[178:179], v[176:177], 0, v[174:175]
	s_cbranch_vccnz .LBB0_404
	v_lshl_add_u64 v[154:155], v[178:179], 0, v[182:183]
	s_mov_b64 s[98:99], 0x10000
	v_lshl_add_u64 v[154:155], v[154:155], 0, s[98:99]
	global_load_dwordx4 v[144:147], v[154:155], off
	v_lshl_add_u64 v[154:155], v[154:155], 0, s[98:99]
	global_load_dwordx4 v[144:147], v[154:155], off
	v_lshl_add_u64 v[154:155], v[154:155], 0, s[98:99]
	global_load_dwordx4 v[144:147], v[154:155], off
	s_mov_b64 s[98:99], 0x50000
	v_lshl_add_u64 v[154:155], v[154:155], 0, s[98:99]
	s_mov_b64 s[98:99], 0x10000
	global_load_dwordx4 v[144:147], v[154:155], off
	v_lshl_add_u64 v[154:155], v[154:155], 0, s[98:99]
	global_load_dwordx4 v[144:147], v[154:155], off
	v_lshl_add_u64 v[154:155], v[154:155], 0, s[98:99]
	global_load_dwordx4 v[144:147], v[154:155], off
	v_lshl_add_u64 v[154:155], v[154:155], 0, s[98:99]
	global_load_dwordx4 v[144:147], v[154:155], off
	s_waitcnt vmcnt(0)
	v_lshl_add_u64 v[144:145], v[178:179], 0, v[182:183]
	global_load_dwordx4 v[144:147], v[144:145], off
	s_waitcnt vmcnt(0)
	v_lshlrev_b32_e32 v148, 16, v144
	v_and_b32_e32 v149, 0xffff0000, v144
	v_lshlrev_b32_e32 v150, 16, v145
	v_and_b32_e32 v151, 0xffff0000, v145
	v_lshlrev_b32_e32 v144, 16, v146
	v_and_b32_e32 v145, 0xffff0000, v146
	v_lshlrev_b32_e32 v146, 16, v147
	v_and_b32_e32 v147, 0xffff0000, v147
